# P0 rebalance (hy_in weight transpose only on blocks without mod/filt_mlp items), hy_transpose rewritten with 16-byte accesses and double-buffered LDS, final norm rewritten (all loads up front, DPP red
# speedup vs baseline: 1.1037x; 1.0112x over previous
.LBB0_320:
	v_mov_b32_e32 v4, v176
	s_mov_b32 s0, s94
	s_sub_i32 s6, s84, s6
	s_add_i32 s0, s0, s6
	s_ashr_i32 s1, s0, 31
	s_abs_i32 s0, s0
	s_mul_hi_u32 s2, s0, s50
	s_mul_i32 s2, s2, s49
	s_sub_i32 s0, s0, s2
	s_sub_i32 s2, s0, s49
	s_cmp_ge_u32 s0, s49
	s_cselect_b32 s0, s2, s0
	s_sub_i32 s2, s0, s49
	s_cmp_ge_u32 s0, s49
	s_cselect_b32 s0, s2, s0
	s_xor_b32 s0, s0, s1
	s_sub_i32 s8, s0, s1
	s_mov_b32 s100, s84
	s_cmpk_eq_i32 s84, 0x200
	s_cbranch_scc0 .Lp0bal_skip
	s_sub_i32 s8, s94, 0x150
	s_movk_i32 s100, 0xb0
	s_cmp_lt_i32 s8, 0
	s_cselect_b32 s8, 0x400, s8
.Lp0bal_skip:
	s_cmpk_gt_i32 s8, 0x3ff
	s_cbranch_scc1 .LBB0_355
	v_and_b32_e32 v8, 63, v4
	v_ashrrev_i32_e32 v9, 6, v4
	v_lshlrev_b32_e32 v0, 2, v8
	v_mov_b32_e32 v1, 0
	v_lshl_add_u64 v[2:3], s[52:53], 0, v[0:1]
	v_lshlrev_b32_e32 v0, 2, v9
	s_movk_i32 s0, 0x104
	v_mad_u32_u24 v10, v8, s0, v0
	v_ashrrev_i32_e32 v11, 2, v4
	v_lshlrev_b32_e32 v0, 4, v4
	v_and_b32_e32 v0, 48, v0
	v_mul_lo_u32 v4, v11, s0
	v_lshl_add_u32 v12, v0, 2, v4
	s_lshl_b32 s9, s8, 6
	s_lshl_b32 s10, s100, 6
	s_movk_i32 s11, 0x1000
	v_lshlrev_b32_e32 v0, 1, v0
	s_branch .LBB0_323
.LBB0_322:
	s_or_b64 exec, exec, s[4:5]
	s_waitcnt vmcnt(0)
	ds_write2_b32 v10, v13, v15 offset1:4
	ds_write2_b32 v10, v14, v17 offset0:8 offset1:12
	ds_write2_b32 v10, v16, v19 offset0:16 offset1:20
	ds_write2_b32 v10, v18, v21 offset0:24 offset1:28
	ds_write2_b32 v10, v20, v23 offset0:32 offset1:36
	ds_write2_b32 v10, v22, v25 offset0:40 offset1:44
	ds_write2_b32 v10, v24, v27 offset0:48 offset1:52
	ds_write2_b32 v10, v26, v28 offset0:56 offset1:60
	s_waitcnt lgkmcnt(0)
	s_barrier
	ds_read2_b32 v[4:5], v12 offset1:1
	ds_read2_b32 v[6:7], v12 offset0:2 offset1:3
	ds_read2_b32 v[14:15], v12 offset0:4 offset1:5
	ds_read2_b32 v[16:17], v12 offset0:6 offset1:7
	s_sub_i32 s0, 0, s3
	s_waitcnt lgkmcnt(3)
	v_cvt_pk_bf16_f32 v4, v4, v5
	s_waitcnt lgkmcnt(2)
	v_cvt_pk_bf16_f32 v5, v6, v7
	s_waitcnt lgkmcnt(1)
	v_cvt_pk_bf16_f32 v6, v14, v15
	ds_read2_b32 v[14:15], v12 offset0:8 offset1:9
	ds_read2_b32 v[18:19], v12 offset0:10 offset1:11
	ds_read2_b32 v[20:21], v12 offset0:12 offset1:13
	ds_read2_b32 v[22:23], v12 offset0:14 offset1:15
	s_add_i32 s0, s0, s9
	s_waitcnt lgkmcnt(3)
	v_cvt_pk_bf16_f32 v14, v14, v15
	s_waitcnt lgkmcnt(2)
	v_cvt_pk_bf16_f32 v15, v18, v19
	v_add_u32_e32 v18, s0, v11
	v_ashrrev_i32_e32 v19, 31, v18
	v_readlane_b32 s12, v252, 18
	v_lshlrev_b64 v[18:19], 11, v[18:19]
	v_readlane_b32 s26, v252, 32
	v_readlane_b32 s27, v252, 33
	s_ashr_i32 s3, s2, 31
	s_add_i32 s8, s8, s100
	v_lshl_add_u64 v[18:19], s[26:27], 0, v[18:19]
	v_lshl_add_u64 v[18:19], s[2:3], 1, v[18:19]
	s_add_i32 s9, s9, s10
	v_cvt_pk_bf16_f32 v7, v16, v17
	s_waitcnt lgkmcnt(1)
	v_cvt_pk_bf16_f32 v16, v20, v21
	s_waitcnt lgkmcnt(0)
	v_cvt_pk_bf16_f32 v17, v22, v23
	v_lshl_add_u64 v[18:19], v[18:19], 0, v[0:1]
	s_cmpk_lt_i32 s8, 0x400
	v_readlane_b32 s13, v252, 19
	v_readlane_b32 s14, v252, 20
	v_readlane_b32 s15, v252, 21
	v_readlane_b32 s16, v252, 22
	v_readlane_b32 s17, v252, 23
	v_readlane_b32 s18, v252, 24
	v_readlane_b32 s19, v252, 25
	v_readlane_b32 s20, v252, 26
	v_readlane_b32 s21, v252, 27
	v_readlane_b32 s22, v252, 28
	v_readlane_b32 s23, v252, 29
	v_readlane_b32 s24, v252, 30
	v_readlane_b32 s25, v252, 31
	global_store_dwordx4 v[18:19], v[4:7], off
	global_store_dwordx4 v[18:19], v[14:17], off offset:16
	s_cbranch_scc0 .LBB0_355

.LBB0_769:
	s_or_b64 exec, exec, s[0:1]
	s_waitcnt lgkmcnt(0)
	v_mov_b32_e32 v0, v176
	s_mov_b32 s4, s94
	s_barrier
	v_readlane_b32 s1, v254, 41
	s_nop 3
	s_cmpk_eq_i32 s1, 0x200
	s_cbranch_scc1 .Lhyt_fast
	s_cmpk_gt_i32 s4, 0xbff
	s_cbranch_scc1 .LBB0_788
	v_and_b32_e32 v1, 63, v0
	v_readlane_b32 s0, v254, 31
	v_lshlrev_b32_e32 v64, 1, v1
	v_readlane_b32 s1, v254, 32
	v_mul_i32_i24_e32 v2, 0xffffff7e, v1
	v_mul_u32_u24_e32 v11, 0x84, v1
	v_lshl_add_u64 v[8:9], s[0:1], 0, v[64:65]
	s_movk_i32 s0, 0x84
	v_mad_u32_u24 v10, v1, s0, v2
	v_max_i32_e32 v1, 0xf00, v0
	v_sub_u32_e32 v1, v1, v0
	v_add_u32_e32 v1, 0xff, v1
	v_lshrrev_b32_e32 v2, 8, v1
	v_add_u32_e32 v4, 1, v2
	v_and_b32_e32 v16, 0x1fffffc, v4
	v_cmp_gt_i32_e32 vcc, s92, v0
	v_lshl_add_u64 v[12:13], s[88:89], 0, v[64:65]
	v_cmp_lt_u32_e64 s[0:1], s97, v1
	v_lshl_add_u32 v17, v16, 8, v0
	v_add_u32_e32 v3, 0x300, v0
	v_add_u32_e32 v2, 0x200, v0
	v_add_u32_e32 v1, 0x100, v0
	v_cmp_ne_u32_e64 s[36:37], v4, v16
	s_branch .LBB0_772

.Lhyt_fast:
	v_readlane_b32 s0, v254, 31
	v_readlane_b32 s1, v254, 32
	v_lshrrev_b32_e32 v28, 2, v176
	v_and_b32_e32 v29, 3, v176
	v_lshlrev_b32_e32 v30, 5, v29
	v_mul_u32_u24_e32 v24, 0x6000, v28
	v_add_u32_e32 v24, v24, v30
	v_mul_u32_u24_e32 v25, 2304, v29
	v_lshl_add_u32 v25, v28, 1, v25
	v_mul_u32_u24_e32 v26, 144, v28
	v_add_u32_e32 v26, v26, v30
	v_lshl_add_u32 v27, v28, 11, v30
	s_and_b32 s2, s94, 15
	s_lshr_b32 s3, s94, 4
	s_lshl_b32 s3, s3, 6
	s_mul_i32 s4, s2, 0x180000
	s_lshl_b32 s5, s3, 1
	s_add_u32 s4, s4, s5
	s_add_u32 s6, s0, s4
	s_addc_u32 s7, s1, 0
	s_lshl_b32 s4, s3, 11
	s_lshl_b32 s5, s2, 7
	s_add_u32 s4, s4, s5
	s_add_u32 s8, s88, s4
	s_addc_u32 s9, s89, 0
	global_load_dwordx4 v[0:3], v24, s[6:7]
	global_load_dwordx4 v[4:7], v24, s[6:7] offset:16
	s_add_u32 s6, s6, 0x1000
	s_addc_u32 s7, s7, 0
	global_load_dwordx4 v[8:11], v24, s[6:7]
	global_load_dwordx4 v[12:15], v24, s[6:7] offset:16
	s_add_u32 s6, s6, 0x1000
	s_addc_u32 s7, s7, 0
	s_waitcnt vmcnt(2)
	ds_write_b16 v25, v0 offset:0
	ds_write_b16_d16_hi v25, v0 offset:144
	ds_write_b16 v25, v1 offset:288
	ds_write_b16_d16_hi v25, v1 offset:432
	ds_write_b16 v25, v2 offset:576
	ds_write_b16_d16_hi v25, v2 offset:720
	ds_write_b16 v25, v3 offset:864
	ds_write_b16_d16_hi v25, v3 offset:1008
	ds_write_b16 v25, v4 offset:1152
	ds_write_b16_d16_hi v25, v4 offset:1296
	ds_write_b16 v25, v5 offset:1440
	ds_write_b16_d16_hi v25, v5 offset:1584
	ds_write_b16 v25, v6 offset:1728
	ds_write_b16_d16_hi v25, v6 offset:1872
	ds_write_b16 v25, v7 offset:2016
	ds_write_b16_d16_hi v25, v7 offset:2160
	s_waitcnt lgkmcnt(0)
	s_barrier
	ds_read_b128 v[16:19], v26 offset:0
	ds_read_b128 v[20:23], v26 offset:16
	s_waitcnt lgkmcnt(0)
	global_store_dwordx4 v27, v[16:19], s[8:9]
	global_store_dwordx4 v27, v[20:23], s[8:9] offset:16
	s_add_u32 s8, s8, 0x400000
	s_addc_u32 s9, s9, 0
	global_load_dwordx4 v[0:3], v24, s[6:7]
	global_load_dwordx4 v[4:7], v24, s[6:7] offset:16
	s_add_u32 s6, s6, 0x1000
	s_addc_u32 s7, s7, 0
	s_waitcnt vmcnt(4)
	ds_write_b16 v25, v8 offset:9216
	ds_write_b16_d16_hi v25, v8 offset:9360
	ds_write_b16 v25, v9 offset:9504
	ds_write_b16_d16_hi v25, v9 offset:9648
	ds_write_b16 v25, v10 offset:9792
	ds_write_b16_d16_hi v25, v10 offset:9936
	ds_write_b16 v25, v11 offset:10080
	ds_write_b16_d16_hi v25, v11 offset:10224
	ds_write_b16 v25, v12 offset:10368
	ds_write_b16_d16_hi v25, v12 offset:10512
	ds_write_b16 v25, v13 offset:10656
	ds_write_b16_d16_hi v25, v13 offset:10800
	ds_write_b16 v25, v14 offset:10944
	ds_write_b16_d16_hi v25, v14 offset:11088
	ds_write_b16 v25, v15 offset:11232
	ds_write_b16_d16_hi v25, v15 offset:11376
	s_waitcnt lgkmcnt(0)
	s_barrier
	ds_read_b128 v[16:19], v26 offset:9216
	ds_read_b128 v[20:23], v26 offset:9232
	s_waitcnt lgkmcnt(0)
	global_store_dwordx4 v27, v[16:19], s[8:9]
	global_store_dwordx4 v27, v[20:23], s[8:9] offset:16
	s_add_u32 s8, s8, 0x400000
	s_addc_u32 s9, s9, 0
	global_load_dwordx4 v[8:11], v24, s[6:7]
	global_load_dwordx4 v[12:15], v24, s[6:7] offset:16
	s_add_u32 s6, s6, 0x1000
	s_addc_u32 s7, s7, 0
	s_waitcnt vmcnt(4)
	ds_write_b16 v25, v0 offset:0
	ds_write_b16_d16_hi v25, v0 offset:144
	ds_write_b16 v25, v1 offset:288
	ds_write_b16_d16_hi v25, v1 offset:432
	ds_write_b16 v25, v2 offset:576
	ds_write_b16_d16_hi v25, v2 offset:720
	ds_write_b16 v25, v3 offset:864
	ds_write_b16_d16_hi v25, v3 offset:1008
	ds_write_b16 v25, v4 offset:1152
	ds_write_b16_d16_hi v25, v4 offset:1296
	ds_write_b16 v25, v5 offset:1440
	ds_write_b16_d16_hi v25, v5 offset:1584
	ds_write_b16 v25, v6 offset:1728
	ds_write_b16_d16_hi v25, v6 offset:1872
	ds_write_b16 v25, v7 offset:2016
	ds_write_b16_d16_hi v25, v7 offset:2160
	s_waitcnt lgkmcnt(0)
	s_barrier
	ds_read_b128 v[16:19], v26 offset:0
	ds_read_b128 v[20:23], v26 offset:16
	s_waitcnt lgkmcnt(0)
	global_store_dwordx4 v27, v[16:19], s[8:9]
	global_store_dwordx4 v27, v[20:23], s[8:9] offset:16
	s_add_u32 s8, s8, 0x400000
	s_addc_u32 s9, s9, 0
	global_load_dwordx4 v[0:3], v24, s[6:7]
	global_load_dwordx4 v[4:7], v24, s[6:7] offset:16
	s_add_u32 s6, s6, 0x1000
	s_addc_u32 s7, s7, 0
	s_waitcnt vmcnt(4)
	ds_write_b16 v25, v8 offset:9216
	ds_write_b16_d16_hi v25, v8 offset:9360
	ds_write_b16 v25, v9 offset:9504
	ds_write_b16_d16_hi v25, v9 offset:9648
	ds_write_b16 v25, v10 offset:9792
	ds_write_b16_d16_hi v25, v10 offset:9936
	ds_write_b16 v25, v11 offset:10080
	ds_write_b16_d16_hi v25, v11 offset:10224
	ds_write_b16 v25, v12 offset:10368
	ds_write_b16_d16_hi v25, v12 offset:10512
	ds_write_b16 v25, v13 offset:10656
	ds_write_b16_d16_hi v25, v13 offset:10800
	ds_write_b16 v25, v14 offset:10944
	ds_write_b16_d16_hi v25, v14 offset:11088
	ds_write_b16 v25, v15 offset:11232
	ds_write_b16_d16_hi v25, v15 offset:11376
	s_waitcnt lgkmcnt(0)
	s_barrier
	ds_read_b128 v[16:19], v26 offset:9216
	ds_read_b128 v[20:23], v26 offset:9232
	s_waitcnt lgkmcnt(0)
	global_store_dwordx4 v27, v[16:19], s[8:9]
	global_store_dwordx4 v27, v[20:23], s[8:9] offset:16
	s_add_u32 s8, s8, 0x400000
	s_addc_u32 s9, s9, 0
	global_load_dwordx4 v[8:11], v24, s[6:7]
	global_load_dwordx4 v[12:15], v24, s[6:7] offset:16
	s_add_u32 s6, s6, 0x1000
	s_addc_u32 s7, s7, 0
	s_waitcnt vmcnt(4)
	ds_write_b16 v25, v0 offset:0
	ds_write_b16_d16_hi v25, v0 offset:144
	ds_write_b16 v25, v1 offset:288
	ds_write_b16_d16_hi v25, v1 offset:432
	ds_write_b16 v25, v2 offset:576
	ds_write_b16_d16_hi v25, v2 offset:720
	ds_write_b16 v25, v3 offset:864
	ds_write_b16_d16_hi v25, v3 offset:1008
	ds_write_b16 v25, v4 offset:1152
	ds_write_b16_d16_hi v25, v4 offset:1296
	ds_write_b16 v25, v5 offset:1440
	ds_write_b16_d16_hi v25, v5 offset:1584
	ds_write_b16 v25, v6 offset:1728
	ds_write_b16_d16_hi v25, v6 offset:1872
	ds_write_b16 v25, v7 offset:2016
	ds_write_b16_d16_hi v25, v7 offset:2160
	s_waitcnt lgkmcnt(0)
	s_barrier
	ds_read_b128 v[16:19], v26 offset:0
	ds_read_b128 v[20:23], v26 offset:16
	s_waitcnt lgkmcnt(0)
	global_store_dwordx4 v27, v[16:19], s[8:9]
	global_store_dwordx4 v27, v[20:23], s[8:9] offset:16
	s_add_u32 s8, s8, 0x400000
	s_addc_u32 s9, s9, 0
	s_waitcnt vmcnt(2)
	ds_write_b16 v25, v8 offset:9216
	ds_write_b16_d16_hi v25, v8 offset:9360
	ds_write_b16 v25, v9 offset:9504
	ds_write_b16_d16_hi v25, v9 offset:9648
	ds_write_b16 v25, v10 offset:9792
	ds_write_b16_d16_hi v25, v10 offset:9936
	ds_write_b16 v25, v11 offset:10080
	ds_write_b16_d16_hi v25, v11 offset:10224
	ds_write_b16 v25, v12 offset:10368
	ds_write_b16_d16_hi v25, v12 offset:10512
	ds_write_b16 v25, v13 offset:10656
	ds_write_b16_d16_hi v25, v13 offset:10800
	ds_write_b16 v25, v14 offset:10944
	ds_write_b16_d16_hi v25, v14 offset:11088
	ds_write_b16 v25, v15 offset:11232
	ds_write_b16_d16_hi v25, v15 offset:11376
	s_waitcnt lgkmcnt(0)
	s_barrier
	ds_read_b128 v[16:19], v26 offset:9216
	ds_read_b128 v[20:23], v26 offset:9232
	s_waitcnt lgkmcnt(0)
	global_store_dwordx4 v27, v[16:19], s[8:9]
	global_store_dwordx4 v27, v[20:23], s[8:9] offset:16
	s_branch .LBB0_788

.LBB0_1502:
	v_readlane_b32 s1, v254, 41
	s_nop 3
	s_cmpk_eq_i32 s1, 0x200
	s_cbranch_scc1 .Lfnorm_fast
	s_movk_i32 s0, 0x3000
	v_ashrrev_i32_e32 v0, 6, v176
	v_lshl_add_u32 v0, s94, 2, v0
	v_cmp_gt_i32_e32 vcc, s0, v0
	s_and_saveexec_b64 s[0:1], vcc
	v_readlane_b32 s16, v254, 38
	v_readlane_b32 s17, v254, 39
	s_cbranch_execz .LBB0_1505
	v_lshlrev_b32_e32 v1, 4, v176
	v_cmp_lt_i32_e32 vcc, v191, v185
	v_and_b32_e32 v4, 0x3f0, v1
	v_readlane_b32 s0, v253, 18
	v_cndmask_b32_e32 v1, v183, v191, vcc
	v_cmp_lt_i32_e32 vcc, v190, v185
	v_lshlrev_b32_e32 v6, 2, v1
	v_mov_b32_e32 v5, 0
	v_cndmask_b32_e32 v1, v183, v190, vcc
	v_cmp_lt_i32_e32 vcc, v189, v185
	v_lshlrev_b32_e32 v7, 2, v1
	v_readlane_b32 s1, v253, 19
	v_cndmask_b32_e32 v1, v183, v189, vcc
	v_cmp_lt_i32_e32 vcc, v188, v185
	v_lshlrev_b32_e32 v8, 2, v1
	v_readlane_b32 s2, v253, 20
	v_cndmask_b32_e32 v1, v183, v188, vcc
	v_cmp_lt_i32_e32 vcc, v187, v185
	v_lshlrev_b32_e32 v9, 2, v1
	v_readlane_b32 s3, v253, 21
	v_cndmask_b32_e32 v1, v183, v187, vcc
	v_cmp_lt_i32_e32 vcc, v186, v185
	v_lshlrev_b32_e32 v10, 2, v1
	v_lshl_add_u64 v[2:3], s[0:1], 0, v[4:5]
	v_cndmask_b32_e32 v1, v183, v186, vcc
	v_lshlrev_b32_e32 v11, 2, v1
	v_lshl_add_u64 v[4:5], s[86:87], 0, v[4:5]
	s_mov_b64 s[0:1], 0
	v_mov_b32_e32 v12, 0x358637bd
	s_mov_b32 s2, 0x800000
	s_movk_i32 s3, 0x2fff
	v_readlane_b32 s4, v253, 22
	v_readlane_b32 s5, v253, 23
	v_readlane_b32 s6, v253, 24
	v_readlane_b32 s7, v253, 25
	v_readlane_b32 s8, v253, 26
	v_readlane_b32 s9, v253, 27
	v_readlane_b32 s10, v253, 28
	v_readlane_b32 s11, v253, 29
	v_readlane_b32 s12, v253, 30
	v_readlane_b32 s13, v253, 31
	v_readlane_b32 s14, v253, 32
	v_readlane_b32 s15, v253, 33

.Lfnorm_fast:
	v_readlane_b32 s0, v253, 18
	v_readlane_b32 s1, v253, 19
	v_and_b32_e32 v0, 63, v176
	v_lshlrev_b32_e32 v0, 4, v0
	v_lshrrev_b32_e32 v1, 6, v176
	s_nop 0
	v_readfirstlane_b32 s6, v1
	global_load_dwordx4 v[100:103], v0, s[0:1]
	global_load_dwordx4 v[104:107], v0, s[0:1] offset:1024
	global_load_dwordx4 v[108:111], v0, s[0:1] offset:2048
	global_load_dwordx4 v[112:115], v0, s[0:1] offset:3072
	s_lshl_b32 s7, s94, 2
	s_add_i32 s7, s7, s6
	s_lshl_b32 s7, s7, 12
	s_add_u32 s2, s86, s7
	s_addc_u32 s3, s87, 0
	s_mov_b32 s4, s2
	s_mov_b32 s5, s3
	global_load_dwordx4 v[4:7], v0, s[2:3] nt
	global_load_dwordx4 v[8:11], v0, s[2:3] offset:1024 nt
	global_load_dwordx4 v[12:15], v0, s[2:3] offset:2048 nt
	global_load_dwordx4 v[16:19], v0, s[2:3] offset:3072 nt
	s_add_u32 s2, s2, 0x800000
	s_addc_u32 s3, s3, 0
	global_load_dwordx4 v[20:23], v0, s[2:3] nt
	global_load_dwordx4 v[24:27], v0, s[2:3] offset:1024 nt
	global_load_dwordx4 v[28:31], v0, s[2:3] offset:2048 nt
	global_load_dwordx4 v[32:35], v0, s[2:3] offset:3072 nt
	s_add_u32 s2, s2, 0x800000
	s_addc_u32 s3, s3, 0
	global_load_dwordx4 v[36:39], v0, s[2:3] nt
	global_load_dwordx4 v[40:43], v0, s[2:3] offset:1024 nt
	global_load_dwordx4 v[44:47], v0, s[2:3] offset:2048 nt
	global_load_dwordx4 v[48:51], v0, s[2:3] offset:3072 nt
	s_add_u32 s2, s2, 0x800000
	s_addc_u32 s3, s3, 0
	global_load_dwordx4 v[52:55], v0, s[2:3] nt
	global_load_dwordx4 v[56:59], v0, s[2:3] offset:1024 nt
	global_load_dwordx4 v[60:63], v0, s[2:3] offset:2048 nt
	global_load_dwordx4 v[64:67], v0, s[2:3] offset:3072 nt
	s_add_u32 s2, s2, 0x800000
	s_addc_u32 s3, s3, 0
	global_load_dwordx4 v[68:71], v0, s[2:3] nt
	global_load_dwordx4 v[72:75], v0, s[2:3] offset:1024 nt
	global_load_dwordx4 v[76:79], v0, s[2:3] offset:2048 nt
	global_load_dwordx4 v[80:83], v0, s[2:3] offset:3072 nt
	s_add_u32 s2, s2, 0x800000
	s_addc_u32 s3, s3, 0
	global_load_dwordx4 v[84:87], v0, s[2:3] nt
	global_load_dwordx4 v[88:91], v0, s[2:3] offset:1024 nt
	global_load_dwordx4 v[92:95], v0, s[2:3] offset:2048 nt
	global_load_dwordx4 v[96:99], v0, s[2:3] offset:3072 nt
	v_mov_b32_e32 v120, 0x358637bd
	s_waitcnt vmcnt(20)
	v_pk_mul_f32 v[122:123], v[4:5], v[4:5]
	v_pk_fma_f32 v[122:123], v[6:7], v[6:7], v[122:123]
	v_pk_fma_f32 v[122:123], v[8:9], v[8:9], v[122:123]
	v_pk_fma_f32 v[122:123], v[10:11], v[10:11], v[122:123]
	v_pk_fma_f32 v[122:123], v[12:13], v[12:13], v[122:123]
	v_pk_fma_f32 v[122:123], v[14:15], v[14:15], v[122:123]
	v_pk_fma_f32 v[122:123], v[16:17], v[16:17], v[122:123]
	v_pk_fma_f32 v[122:123], v[18:19], v[18:19], v[122:123]
	v_add_f32_e32 v122, v122, v123
	s_nop 1
	v_add_f32_dpp v122, v122, v122 row_ror:8 row_mask:0xf bank_mask:0xf
	s_nop 1
	v_add_f32_dpp v122, v122, v122 row_ror:4 row_mask:0xf bank_mask:0xf
	s_nop 1
	v_add_f32_dpp v122, v122, v122 row_ror:2 row_mask:0xf bank_mask:0xf
	s_nop 1
	v_add_f32_dpp v122, v122, v122 row_ror:1 row_mask:0xf bank_mask:0xf
	v_mov_b32_e32 v123, v122
	s_nop 1
	v_permlane16_swap_b32 v122, v123
	v_add_f32_e32 v122, v122, v123
	v_mov_b32_e32 v123, v122
	s_nop 1
	v_permlane32_swap_b32 v122, v123
	v_add_f32_e32 v122, v122, v123
	v_fmamk_f32 v122, v122, 0x3a800000, v120
	v_mul_f32_e32 v123, 0x4b800000, v122
	v_cmp_gt_f32_e32 vcc, 0x800000, v122
	s_nop 1
	v_cndmask_b32_e32 v122, v122, v123, vcc
	v_rsq_f32_e32 v124, v122
	s_nop 0
	v_mul_f32_e32 v123, 0x45800000, v124
	v_cndmask_b32_e32 v124, v124, v123, vcc
	v_pk_mul_f32 v[4:5], v[4:5], v[124:125] op_sel_hi:[1,0]
	v_pk_mul_f32 v[6:7], v[6:7], v[124:125] op_sel_hi:[1,0]
	v_pk_mul_f32 v[4:5], v[100:101], v[4:5]
	v_pk_mul_f32 v[6:7], v[102:103], v[6:7]
	global_store_dwordx4 v0, v[4:7], s[4:5] nt
	v_pk_mul_f32 v[8:9], v[8:9], v[124:125] op_sel_hi:[1,0]
	v_pk_mul_f32 v[10:11], v[10:11], v[124:125] op_sel_hi:[1,0]
	v_pk_mul_f32 v[8:9], v[104:105], v[8:9]
	v_pk_mul_f32 v[10:11], v[106:107], v[10:11]
	global_store_dwordx4 v0, v[8:11], s[4:5] offset:1024 nt
	v_pk_mul_f32 v[12:13], v[12:13], v[124:125] op_sel_hi:[1,0]
	v_pk_mul_f32 v[14:15], v[14:15], v[124:125] op_sel_hi:[1,0]
	v_pk_mul_f32 v[12:13], v[108:109], v[12:13]
	v_pk_mul_f32 v[14:15], v[110:111], v[14:15]
	global_store_dwordx4 v0, v[12:15], s[4:5] offset:2048 nt
	v_pk_mul_f32 v[16:17], v[16:17], v[124:125] op_sel_hi:[1,0]
	v_pk_mul_f32 v[18:19], v[18:19], v[124:125] op_sel_hi:[1,0]
	v_pk_mul_f32 v[16:17], v[112:113], v[16:17]
	v_pk_mul_f32 v[18:19], v[114:115], v[18:19]
	global_store_dwordx4 v0, v[16:19], s[4:5] offset:3072 nt
	s_add_u32 s4, s4, 0x800000
	s_addc_u32 s5, s5, 0
	s_waitcnt vmcnt(20)
	v_pk_mul_f32 v[122:123], v[20:21], v[20:21]
	v_pk_fma_f32 v[122:123], v[22:23], v[22:23], v[122:123]
	v_pk_fma_f32 v[122:123], v[24:25], v[24:25], v[122:123]
	v_pk_fma_f32 v[122:123], v[26:27], v[26:27], v[122:123]
	v_pk_fma_f32 v[122:123], v[28:29], v[28:29], v[122:123]
	v_pk_fma_f32 v[122:123], v[30:31], v[30:31], v[122:123]
	v_pk_fma_f32 v[122:123], v[32:33], v[32:33], v[122:123]
	v_pk_fma_f32 v[122:123], v[34:35], v[34:35], v[122:123]
	v_add_f32_e32 v122, v122, v123
	s_nop 1
	v_add_f32_dpp v122, v122, v122 row_ror:8 row_mask:0xf bank_mask:0xf
	s_nop 1
	v_add_f32_dpp v122, v122, v122 row_ror:4 row_mask:0xf bank_mask:0xf
	s_nop 1
	v_add_f32_dpp v122, v122, v122 row_ror:2 row_mask:0xf bank_mask:0xf
	s_nop 1
	v_add_f32_dpp v122, v122, v122 row_ror:1 row_mask:0xf bank_mask:0xf
	v_mov_b32_e32 v123, v122
	s_nop 1
	v_permlane16_swap_b32 v122, v123
	v_add_f32_e32 v122, v122, v123
	v_mov_b32_e32 v123, v122
	s_nop 1
	v_permlane32_swap_b32 v122, v123
	v_add_f32_e32 v122, v122, v123
	v_fmamk_f32 v122, v122, 0x3a800000, v120
	v_mul_f32_e32 v123, 0x4b800000, v122
	v_cmp_gt_f32_e32 vcc, 0x800000, v122
	s_nop 1
	v_cndmask_b32_e32 v122, v122, v123, vcc
	v_rsq_f32_e32 v124, v122
	s_nop 0
	v_mul_f32_e32 v123, 0x45800000, v124
	v_cndmask_b32_e32 v124, v124, v123, vcc
	v_pk_mul_f32 v[20:21], v[20:21], v[124:125] op_sel_hi:[1,0]
	v_pk_mul_f32 v[22:23], v[22:23], v[124:125] op_sel_hi:[1,0]
	v_pk_mul_f32 v[20:21], v[100:101], v[20:21]
	v_pk_mul_f32 v[22:23], v[102:103], v[22:23]
	global_store_dwordx4 v0, v[20:23], s[4:5] nt
	v_pk_mul_f32 v[24:25], v[24:25], v[124:125] op_sel_hi:[1,0]
	v_pk_mul_f32 v[26:27], v[26:27], v[124:125] op_sel_hi:[1,0]
	v_pk_mul_f32 v[24:25], v[104:105], v[24:25]
	v_pk_mul_f32 v[26:27], v[106:107], v[26:27]
	global_store_dwordx4 v0, v[24:27], s[4:5] offset:1024 nt
	v_pk_mul_f32 v[28:29], v[28:29], v[124:125] op_sel_hi:[1,0]
	v_pk_mul_f32 v[30:31], v[30:31], v[124:125] op_sel_hi:[1,0]
	v_pk_mul_f32 v[28:29], v[108:109], v[28:29]
	v_pk_mul_f32 v[30:31], v[110:111], v[30:31]
	global_store_dwordx4 v0, v[28:31], s[4:5] offset:2048 nt
	v_pk_mul_f32 v[32:33], v[32:33], v[124:125] op_sel_hi:[1,0]
	v_pk_mul_f32 v[34:35], v[34:35], v[124:125] op_sel_hi:[1,0]
	v_pk_mul_f32 v[32:33], v[112:113], v[32:33]
	v_pk_mul_f32 v[34:35], v[114:115], v[34:35]
	global_store_dwordx4 v0, v[32:35], s[4:5] offset:3072 nt
	s_add_u32 s4, s4, 0x800000
	s_addc_u32 s5, s5, 0
	s_waitcnt vmcnt(20)
	v_pk_mul_f32 v[122:123], v[36:37], v[36:37]
	v_pk_fma_f32 v[122:123], v[38:39], v[38:39], v[122:123]
	v_pk_fma_f32 v[122:123], v[40:41], v[40:41], v[122:123]
	v_pk_fma_f32 v[122:123], v[42:43], v[42:43], v[122:123]
	v_pk_fma_f32 v[122:123], v[44:45], v[44:45], v[122:123]
	v_pk_fma_f32 v[122:123], v[46:47], v[46:47], v[122:123]
	v_pk_fma_f32 v[122:123], v[48:49], v[48:49], v[122:123]
	v_pk_fma_f32 v[122:123], v[50:51], v[50:51], v[122:123]
	v_add_f32_e32 v122, v122, v123
	s_nop 1
	v_add_f32_dpp v122, v122, v122 row_ror:8 row_mask:0xf bank_mask:0xf
	s_nop 1
	v_add_f32_dpp v122, v122, v122 row_ror:4 row_mask:0xf bank_mask:0xf
	s_nop 1
	v_add_f32_dpp v122, v122, v122 row_ror:2 row_mask:0xf bank_mask:0xf
	s_nop 1
	v_add_f32_dpp v122, v122, v122 row_ror:1 row_mask:0xf bank_mask:0xf
	v_mov_b32_e32 v123, v122
	s_nop 1
	v_permlane16_swap_b32 v122, v123
	v_add_f32_e32 v122, v122, v123
	v_mov_b32_e32 v123, v122
	s_nop 1
	v_permlane32_swap_b32 v122, v123
	v_add_f32_e32 v122, v122, v123
	v_fmamk_f32 v122, v122, 0x3a800000, v120
	v_mul_f32_e32 v123, 0x4b800000, v122
	v_cmp_gt_f32_e32 vcc, 0x800000, v122
	s_nop 1
	v_cndmask_b32_e32 v122, v122, v123, vcc
	v_rsq_f32_e32 v124, v122
	s_nop 0
	v_mul_f32_e32 v123, 0x45800000, v124
	v_cndmask_b32_e32 v124, v124, v123, vcc
	v_pk_mul_f32 v[36:37], v[36:37], v[124:125] op_sel_hi:[1,0]
	v_pk_mul_f32 v[38:39], v[38:39], v[124:125] op_sel_hi:[1,0]
	v_pk_mul_f32 v[36:37], v[100:101], v[36:37]
	v_pk_mul_f32 v[38:39], v[102:103], v[38:39]
	global_store_dwordx4 v0, v[36:39], s[4:5] nt
	v_pk_mul_f32 v[40:41], v[40:41], v[124:125] op_sel_hi:[1,0]
	v_pk_mul_f32 v[42:43], v[42:43], v[124:125] op_sel_hi:[1,0]
	v_pk_mul_f32 v[40:41], v[104:105], v[40:41]
	v_pk_mul_f32 v[42:43], v[106:107], v[42:43]
	global_store_dwordx4 v0, v[40:43], s[4:5] offset:1024 nt
	v_pk_mul_f32 v[44:45], v[44:45], v[124:125] op_sel_hi:[1,0]
	v_pk_mul_f32 v[46:47], v[46:47], v[124:125] op_sel_hi:[1,0]
	v_pk_mul_f32 v[44:45], v[108:109], v[44:45]
	v_pk_mul_f32 v[46:47], v[110:111], v[46:47]
	global_store_dwordx4 v0, v[44:47], s[4:5] offset:2048 nt
	v_pk_mul_f32 v[48:49], v[48:49], v[124:125] op_sel_hi:[1,0]
	v_pk_mul_f32 v[50:51], v[50:51], v[124:125] op_sel_hi:[1,0]
	v_pk_mul_f32 v[48:49], v[112:113], v[48:49]
	v_pk_mul_f32 v[50:51], v[114:115], v[50:51]
	global_store_dwordx4 v0, v[48:51], s[4:5] offset:3072 nt
	s_add_u32 s4, s4, 0x800000
	s_addc_u32 s5, s5, 0
	s_waitcnt vmcnt(20)
	v_pk_mul_f32 v[122:123], v[52:53], v[52:53]
	v_pk_fma_f32 v[122:123], v[54:55], v[54:55], v[122:123]
	v_pk_fma_f32 v[122:123], v[56:57], v[56:57], v[122:123]
	v_pk_fma_f32 v[122:123], v[58:59], v[58:59], v[122:123]
	v_pk_fma_f32 v[122:123], v[60:61], v[60:61], v[122:123]
	v_pk_fma_f32 v[122:123], v[62:63], v[62:63], v[122:123]
	v_pk_fma_f32 v[122:123], v[64:65], v[64:65], v[122:123]
	v_pk_fma_f32 v[122:123], v[66:67], v[66:67], v[122:123]
	v_add_f32_e32 v122, v122, v123
	s_nop 1
	v_add_f32_dpp v122, v122, v122 row_ror:8 row_mask:0xf bank_mask:0xf
	s_nop 1
	v_add_f32_dpp v122, v122, v122 row_ror:4 row_mask:0xf bank_mask:0xf
	s_nop 1
	v_add_f32_dpp v122, v122, v122 row_ror:2 row_mask:0xf bank_mask:0xf
	s_nop 1
	v_add_f32_dpp v122, v122, v122 row_ror:1 row_mask:0xf bank_mask:0xf
	v_mov_b32_e32 v123, v122
	s_nop 1
	v_permlane16_swap_b32 v122, v123
	v_add_f32_e32 v122, v122, v123
	v_mov_b32_e32 v123, v122
	s_nop 1
	v_permlane32_swap_b32 v122, v123
	v_add_f32_e32 v122, v122, v123
	v_fmamk_f32 v122, v122, 0x3a800000, v120
	v_mul_f32_e32 v123, 0x4b800000, v122
	v_cmp_gt_f32_e32 vcc, 0x800000, v122
	s_nop 1
	v_cndmask_b32_e32 v122, v122, v123, vcc
	v_rsq_f32_e32 v124, v122
	s_nop 0
	v_mul_f32_e32 v123, 0x45800000, v124
	v_cndmask_b32_e32 v124, v124, v123, vcc
	v_pk_mul_f32 v[52:53], v[52:53], v[124:125] op_sel_hi:[1,0]
	v_pk_mul_f32 v[54:55], v[54:55], v[124:125] op_sel_hi:[1,0]
	v_pk_mul_f32 v[52:53], v[100:101], v[52:53]
	v_pk_mul_f32 v[54:55], v[102:103], v[54:55]
	global_store_dwordx4 v0, v[52:55], s[4:5] nt
	v_pk_mul_f32 v[56:57], v[56:57], v[124:125] op_sel_hi:[1,0]
	v_pk_mul_f32 v[58:59], v[58:59], v[124:125] op_sel_hi:[1,0]
	v_pk_mul_f32 v[56:57], v[104:105], v[56:57]
	v_pk_mul_f32 v[58:59], v[106:107], v[58:59]
	global_store_dwordx4 v0, v[56:59], s[4:5] offset:1024 nt
	v_pk_mul_f32 v[60:61], v[60:61], v[124:125] op_sel_hi:[1,0]
	v_pk_mul_f32 v[62:63], v[62:63], v[124:125] op_sel_hi:[1,0]
	v_pk_mul_f32 v[60:61], v[108:109], v[60:61]
	v_pk_mul_f32 v[62:63], v[110:111], v[62:63]
	global_store_dwordx4 v0, v[60:63], s[4:5] offset:2048 nt
	v_pk_mul_f32 v[64:65], v[64:65], v[124:125] op_sel_hi:[1,0]
	v_pk_mul_f32 v[66:67], v[66:67], v[124:125] op_sel_hi:[1,0]
	v_pk_mul_f32 v[64:65], v[112:113], v[64:65]
	v_pk_mul_f32 v[66:67], v[114:115], v[66:67]
	global_store_dwordx4 v0, v[64:67], s[4:5] offset:3072 nt
	s_add_u32 s4, s4, 0x800000
	s_addc_u32 s5, s5, 0
	s_waitcnt vmcnt(20)
	v_pk_mul_f32 v[122:123], v[68:69], v[68:69]
	v_pk_fma_f32 v[122:123], v[70:71], v[70:71], v[122:123]
	v_pk_fma_f32 v[122:123], v[72:73], v[72:73], v[122:123]
	v_pk_fma_f32 v[122:123], v[74:75], v[74:75], v[122:123]
	v_pk_fma_f32 v[122:123], v[76:77], v[76:77], v[122:123]
	v_pk_fma_f32 v[122:123], v[78:79], v[78:79], v[122:123]
	v_pk_fma_f32 v[122:123], v[80:81], v[80:81], v[122:123]
	v_pk_fma_f32 v[122:123], v[82:83], v[82:83], v[122:123]
	v_add_f32_e32 v122, v122, v123
	s_nop 1
	v_add_f32_dpp v122, v122, v122 row_ror:8 row_mask:0xf bank_mask:0xf
	s_nop 1
	v_add_f32_dpp v122, v122, v122 row_ror:4 row_mask:0xf bank_mask:0xf
	s_nop 1
	v_add_f32_dpp v122, v122, v122 row_ror:2 row_mask:0xf bank_mask:0xf
	s_nop 1
	v_add_f32_dpp v122, v122, v122 row_ror:1 row_mask:0xf bank_mask:0xf
	v_mov_b32_e32 v123, v122
	s_nop 1
	v_permlane16_swap_b32 v122, v123
	v_add_f32_e32 v122, v122, v123
	v_mov_b32_e32 v123, v122
	s_nop 1
	v_permlane32_swap_b32 v122, v123
	v_add_f32_e32 v122, v122, v123
	v_fmamk_f32 v122, v122, 0x3a800000, v120
	v_mul_f32_e32 v123, 0x4b800000, v122
	v_cmp_gt_f32_e32 vcc, 0x800000, v122
	s_nop 1
	v_cndmask_b32_e32 v122, v122, v123, vcc
	v_rsq_f32_e32 v124, v122
	s_nop 0
	v_mul_f32_e32 v123, 0x45800000, v124
	v_cndmask_b32_e32 v124, v124, v123, vcc
	v_pk_mul_f32 v[68:69], v[68:69], v[124:125] op_sel_hi:[1,0]
	v_pk_mul_f32 v[70:71], v[70:71], v[124:125] op_sel_hi:[1,0]
	v_pk_mul_f32 v[68:69], v[100:101], v[68:69]
	v_pk_mul_f32 v[70:71], v[102:103], v[70:71]
	global_store_dwordx4 v0, v[68:71], s[4:5] nt
	v_pk_mul_f32 v[72:73], v[72:73], v[124:125] op_sel_hi:[1,0]
	v_pk_mul_f32 v[74:75], v[74:75], v[124:125] op_sel_hi:[1,0]
	v_pk_mul_f32 v[72:73], v[104:105], v[72:73]
	v_pk_mul_f32 v[74:75], v[106:107], v[74:75]
	global_store_dwordx4 v0, v[72:75], s[4:5] offset:1024 nt
	v_pk_mul_f32 v[76:77], v[76:77], v[124:125] op_sel_hi:[1,0]
	v_pk_mul_f32 v[78:79], v[78:79], v[124:125] op_sel_hi:[1,0]
	v_pk_mul_f32 v[76:77], v[108:109], v[76:77]
	v_pk_mul_f32 v[78:79], v[110:111], v[78:79]
	global_store_dwordx4 v0, v[76:79], s[4:5] offset:2048 nt
	v_pk_mul_f32 v[80:81], v[80:81], v[124:125] op_sel_hi:[1,0]
	v_pk_mul_f32 v[82:83], v[82:83], v[124:125] op_sel_hi:[1,0]
	v_pk_mul_f32 v[80:81], v[112:113], v[80:81]
	v_pk_mul_f32 v[82:83], v[114:115], v[82:83]
	global_store_dwordx4 v0, v[80:83], s[4:5] offset:3072 nt
	s_add_u32 s4, s4, 0x800000
	s_addc_u32 s5, s5, 0
	s_waitcnt vmcnt(20)
	v_pk_mul_f32 v[122:123], v[84:85], v[84:85]
	v_pk_fma_f32 v[122:123], v[86:87], v[86:87], v[122:123]
	v_pk_fma_f32 v[122:123], v[88:89], v[88:89], v[122:123]
	v_pk_fma_f32 v[122:123], v[90:91], v[90:91], v[122:123]
	v_pk_fma_f32 v[122:123], v[92:93], v[92:93], v[122:123]
	v_pk_fma_f32 v[122:123], v[94:95], v[94:95], v[122:123]
	v_pk_fma_f32 v[122:123], v[96:97], v[96:97], v[122:123]
	v_pk_fma_f32 v[122:123], v[98:99], v[98:99], v[122:123]
	v_add_f32_e32 v122, v122, v123
	s_nop 1
	v_add_f32_dpp v122, v122, v122 row_ror:8 row_mask:0xf bank_mask:0xf
	s_nop 1
	v_add_f32_dpp v122, v122, v122 row_ror:4 row_mask:0xf bank_mask:0xf
	s_nop 1
	v_add_f32_dpp v122, v122, v122 row_ror:2 row_mask:0xf bank_mask:0xf
	s_nop 1
	v_add_f32_dpp v122, v122, v122 row_ror:1 row_mask:0xf bank_mask:0xf
	v_mov_b32_e32 v123, v122
	s_nop 1
	v_permlane16_swap_b32 v122, v123
	v_add_f32_e32 v122, v122, v123
	v_mov_b32_e32 v123, v122
	s_nop 1
	v_permlane32_swap_b32 v122, v123
	v_add_f32_e32 v122, v122, v123
	v_fmamk_f32 v122, v122, 0x3a800000, v120
	v_mul_f32_e32 v123, 0x4b800000, v122
	v_cmp_gt_f32_e32 vcc, 0x800000, v122
	s_nop 1
	v_cndmask_b32_e32 v122, v122, v123, vcc
	v_rsq_f32_e32 v124, v122
	s_nop 0
	v_mul_f32_e32 v123, 0x45800000, v124
	v_cndmask_b32_e32 v124, v124, v123, vcc
	v_pk_mul_f32 v[84:85], v[84:85], v[124:125] op_sel_hi:[1,0]
	v_pk_mul_f32 v[86:87], v[86:87], v[124:125] op_sel_hi:[1,0]
	v_pk_mul_f32 v[84:85], v[100:101], v[84:85]
	v_pk_mul_f32 v[86:87], v[102:103], v[86:87]
	global_store_dwordx4 v0, v[84:87], s[4:5] nt
	v_pk_mul_f32 v[88:89], v[88:89], v[124:125] op_sel_hi:[1,0]
	v_pk_mul_f32 v[90:91], v[90:91], v[124:125] op_sel_hi:[1,0]
	v_pk_mul_f32 v[88:89], v[104:105], v[88:89]
	v_pk_mul_f32 v[90:91], v[106:107], v[90:91]
	global_store_dwordx4 v0, v[88:91], s[4:5] offset:1024 nt
	v_pk_mul_f32 v[92:93], v[92:93], v[124:125] op_sel_hi:[1,0]
	v_pk_mul_f32 v[94:95], v[94:95], v[124:125] op_sel_hi:[1,0]
	v_pk_mul_f32 v[92:93], v[108:109], v[92:93]
	v_pk_mul_f32 v[94:95], v[110:111], v[94:95]
	global_store_dwordx4 v0, v[92:95], s[4:5] offset:2048 nt
	v_pk_mul_f32 v[96:97], v[96:97], v[124:125] op_sel_hi:[1,0]
	v_pk_mul_f32 v[98:99], v[98:99], v[124:125] op_sel_hi:[1,0]
	v_pk_mul_f32 v[96:97], v[112:113], v[96:97]
	v_pk_mul_f32 v[98:99], v[114:115], v[98:99]
	global_store_dwordx4 v0, v[96:99], s[4:5] offset:3072 nt
	s_endpgm
